# stick-breaking loop: q loads retired before the loop, in-loop waits lgkmcnt only; mixer A: V loads of key tiles 1-3 issued with tile 0
# baseline (speedup 1.0000x reference)
; DI f32x16 mfma32(bf16x8 a, bf16x8 b, f32x16 c) { return __builtin_amdgcn_mfma_f32_32x32x16_bf16(a, b, c, 0, 0, 0); }
; DI int kperm(int r) { return (r & ~12) | ((r & 4) << 1) | ((r & 8) >> 1); }
; DI void attn_A_item(const bf16_t* Q0, const bf16_t* K0, const bf16_t* VT0, const bf16_t* VTXp, const bf16_t* G, bf16_t* Y, int bh, int blk, float Mb, LAS float* Oacc, LAS float* lacc, int tid, int wave, int lane) {
;     ...
;     for (int seg = 0; seg < 3; ++seg) {
;         const int sh = 2 * seg, L = S >> sh;
;         const bf16_t* Vs = (seg == 0) ? (VT0 + (size_t)bh * 64 * S) : (VTXp + (size_t)((seg - 1) * 16 + bh) * 64 * S);
; #pragma unroll 1
;         for (int jq = 0; jq < 2; ++jq) {
;             const int j = 2 * wave + jq, tpr = 16 >> sh, res = j / tpr, jj = j % tpr, m0 = (t0 >> sh) + 32 * jj;
;             const int t = ((m0 + r) << sh) + res;
;             bf16x8 qf[4];
;             load_q(qf, Q0 + ((size_t)bh * S + t) * 64 + 8 * h);
;             f32x16 o0, o1;
; #pragma unroll
;             for (int i = 0; i < 16; ++i) { o0[i] = 0.f; o1[i] = 0.f; }
;             float l = 0.f;
;             const int kfirst = m0 - 128;
;             const float NEGI = -__builtin_inff();
;             bf16x8 kf[5][4];
; #pragma unroll
;             for (int i = 0; i < 5; ++i) {
;                 const int kt = kfirst + 32 * i, ktc = kt < 0 ? 0 : kt;
;                 load_q(kf[i], K0 + ((size_t)bh * S + (((ktc + uperm(kperm(r), seg == 1)) << sh) + res)) * 64 + 8 * h);
;             }
;             f32x16 xs[5];
; #pragma unroll
;             for (int i = 0; i < 5; ++i) {
;                 const float offs = (kfirst + 32 * i < 0) ? NEGI : mb2;
; #pragma unroll
;                 for (int e = 0; e < 16; ++e) xs[i][e] = offs;
; #pragma unroll
;                 for (int sp = 0; sp < 4; ++sp) xs[i] = mfma32(kf[i][sp], qf[sp], xs[i]);
;             }
.LBB0_305:
	s_or_b32 s50, s50, s98
	s_abs_i32 s61, s50
	s_mul_hi_u32 s64, s61, s97
	s_mul_i32 s65, s64, s89
	s_ashr_i32 s60, s50, 31
	s_sub_i32 s61, s61, s65
	s_xor_b32 s60, s60, s88
	s_add_i32 s65, s64, 1
	s_sub_i32 s78, s61, s89
	s_cmp_ge_u32 s61, s89
	s_cselect_b32 s64, s65, s64
	s_cselect_b32 s61, s78, s61
	s_add_i32 s65, s64, 1
	s_cmp_ge_u32 s61, s89
	s_cselect_b32 s61, s65, s64
	s_xor_b32 s61, s61, s60
	s_sub_i32 s84, s61, s60
	s_mul_i32 s60, s84, s1
	s_sub_i32 s50, s50, s60
	s_lshl_b32 s61, s50, 5
	s_add_i32 s61, s61, s92
	v_add_u32_e32 v2, s61, v143
	v_lshlrev_b32_e32 v2, s0, v2
	v_add_u32_e32 v128, s84, v2
	v_ashrrev_i32_e32 v129, 31, v128
	v_lshl_add_u64 v[2:3], s[82:83], 0, v[128:129]
	v_lshlrev_b64 v[2:3], 7, v[2:3]
	s_max_i32 s50, s61, 0x80
	v_lshl_add_u64 v[2:3], v[120:121], 0, v[2:3]
	s_addk_i32 s50, 0xff80
	global_load_dwordx4 v[18:21], v[2:3], off
	global_load_dwordx4 v[22:25], v[2:3], off offset:32
	global_load_dwordx4 v[26:29], v[2:3], off offset:64
	global_load_dwordx4 v[30:33], v[2:3], off offset:96
	v_add_u32_e32 v2, s50, v182
	v_lshlrev_b32_e32 v2, s0, v2
	v_add_u32_e32 v2, s84, v2
	v_ashrrev_i32_e32 v3, 31, v2
	v_lshl_add_u64 v[2:3], s[82:83], 0, v[2:3]
	v_lshlrev_b64 v[2:3], 7, v[2:3]
	v_lshl_add_u64 v[2:3], v[122:123], 0, v[2:3]
	global_load_dwordx4 v[78:81], v[2:3], off
	global_load_dwordx4 v[82:85], v[2:3], off offset:32
	global_load_dwordx4 v[86:89], v[2:3], off offset:64
	global_load_dwordx4 v[90:93], v[2:3], off offset:96
	s_max_i32 s60, s61, 0x60
	s_add_i32 s64, s60, 0xffffffa0
	v_add_u32_e32 v2, s64, v182
	v_lshlrev_b32_e32 v2, s0, v2
	v_add_u32_e32 v2, s84, v2
	v_ashrrev_i32_e32 v3, 31, v2
	v_lshl_add_u64 v[2:3], s[82:83], 0, v[2:3]
	v_lshlrev_b64 v[2:3], 7, v[2:3]
	v_lshl_add_u64 v[2:3], v[122:123], 0, v[2:3]
	global_load_dwordx4 v[74:77], v[2:3], off
	global_load_dwordx4 v[70:73], v[2:3], off offset:32
	global_load_dwordx4 v[62:65], v[2:3], off offset:64
	global_load_dwordx4 v[66:69], v[2:3], off offset:96
	s_max_i32 s60, s61, 64
	s_sub_i32 s60, s60, 64
	v_add_u32_e32 v2, s60, v182
	v_lshlrev_b32_e32 v2, s0, v2
	v_add_u32_e32 v2, s84, v2
	v_ashrrev_i32_e32 v3, 31, v2
	v_lshl_add_u64 v[2:3], s[82:83], 0, v[2:3]
	v_lshlrev_b64 v[2:3], 7, v[2:3]
	v_lshl_add_u64 v[2:3], v[122:123], 0, v[2:3]
	global_load_dwordx4 v[58:61], v[2:3], off
	global_load_dwordx4 v[54:57], v[2:3], off offset:32
	global_load_dwordx4 v[50:53], v[2:3], off offset:64
	global_load_dwordx4 v[34:37], v[2:3], off offset:96
	s_max_i32 s65, s61, 32
	s_sub_i32 s86, s65, 32
	v_add_u32_e32 v2, s86, v182
	v_lshlrev_b32_e32 v2, s0, v2
	v_add_u32_e32 v2, s84, v2
	v_ashrrev_i32_e32 v3, 31, v2
	v_lshl_add_u64 v[2:3], s[82:83], 0, v[2:3]
	v_lshlrev_b64 v[2:3], 7, v[2:3]
	v_lshl_add_u64 v[2:3], v[122:123], 0, v[2:3]
	s_max_i32 s78, s61, 0
	global_load_dwordx4 v[114:117], v[2:3], off
	global_load_dwordx4 v[46:49], v[2:3], off offset:32
	global_load_dwordx4 v[42:45], v[2:3], off offset:64
	global_load_dwordx4 v[38:41], v[2:3], off offset:96
	v_add_u32_e32 v2, s78, v182
	v_lshlrev_b32_e32 v2, s0, v2
	v_add_u32_e32 v2, s84, v2
	v_ashrrev_i32_e32 v3, 31, v2
	v_lshl_add_u64 v[2:3], s[82:83], 0, v[2:3]
	v_lshlrev_b64 v[2:3], 7, v[2:3]
	s_cmpk_gt_i32 s61, 0x7f
	v_lshl_add_u64 v[2:3], v[122:123], 0, v[2:3]
	s_cselect_b64 vcc, -1, 0
	global_load_dwordx4 v[98:101], v[2:3], off
	global_load_dwordx4 v[102:105], v[2:3], off offset:32
	global_load_dwordx4 v[106:109], v[2:3], off offset:64
	global_load_dwordx4 v[110:113], v[2:3], off offset:96
	v_cndmask_b32_e32 v2, v195, v141, vcc
	v_mov_b32_e32 v3, v2
	v_mov_b32_e32 v4, v2
	v_mov_b32_e32 v5, v2
	v_mov_b32_e32 v6, v2
	v_mov_b32_e32 v7, v2
	v_mov_b32_e32 v8, v2
	v_mov_b32_e32 v9, v2
	v_mov_b32_e32 v10, v2
	v_mov_b32_e32 v11, v2
	v_mov_b32_e32 v12, v2
	v_mov_b32_e32 v13, v2
	v_mov_b32_e32 v14, v2
	v_mov_b32_e32 v15, v2
	v_mov_b32_e32 v16, v2
	v_mov_b32_e32 v17, v2
	s_cmpk_gt_i32 s61, 0x5f
	s_cselect_b64 vcc, -1, 0
	s_cmp_gt_i32 s61, 63
	s_mov_b32 s65, s51
	s_mov_b32 s87, s51
	s_waitcnt vmcnt(19)
	v_mfma_f32_32x32x16_bf16 v[2:17], v[78:81], v[18:21], v[2:17]
	s_waitcnt vmcnt(18)
	v_mfma_f32_32x32x16_bf16 v[2:17], v[82:85], v[22:25], v[2:17]
	v_cndmask_b32_e32 v82, v195, v141, vcc
	v_mov_b32_e32 v83, v82
	v_mov_b32_e32 v84, v82
	v_mov_b32_e32 v85, v82
	v_mov_b32_e32 v94, v82
	v_mov_b32_e32 v95, v82
	v_mov_b32_e32 v96, v82
	s_waitcnt vmcnt(17)
	v_mfma_f32_32x32x16_bf16 v[2:17], v[86:89], v[26:29], v[2:17]
	v_mov_b32_e32 v86, v82
	v_mov_b32_e32 v87, v82
	v_mov_b32_e32 v88, v82
	v_mov_b32_e32 v89, v82
	v_mov_b32_e32 v97, v82
	s_cselect_b64 vcc, -1, 0
	s_cmp_gt_i32 s61, 31
	s_waitcnt vmcnt(16)
	v_mfma_f32_32x32x16_bf16 v[2:17], v[90:93], v[30:33], v[2:17]
	v_mov_b32_e32 v90, v82
	v_mov_b32_e32 v91, v82
	v_mov_b32_e32 v92, v82
	v_mov_b32_e32 v93, v82
	s_waitcnt vmcnt(15)
	s_nop 0
	v_mfma_f32_32x32x16_bf16 v[82:97], v[74:77], v[18:21], v[82:97]
	s_nop 4
	v_exp_f32_e32 v3, v3
	v_exp_f32_e32 v2, v2
	s_nop 0
	v_cndmask_b32_e64 v2, v2, 0, s[10:11]
	s_waitcnt vmcnt(14)
	v_mfma_f32_32x32x16_bf16 v[82:97], v[70:73], v[22:25], v[82:97]
	s_waitcnt vmcnt(13)
	v_mfma_f32_32x32x16_bf16 v[82:97], v[62:65], v[26:29], v[82:97]
	s_waitcnt vmcnt(12)
	v_mfma_f32_32x32x16_bf16 v[82:97], v[66:69], v[30:33], v[82:97]
	v_cndmask_b32_e32 v66, v195, v141, vcc
	v_mov_b32_e32 v67, v66
	v_mov_b32_e32 v68, v66
	v_mov_b32_e32 v69, v66
	v_mov_b32_e32 v70, v66
	v_mov_b32_e32 v71, v66
	v_mov_b32_e32 v72, v66
	v_mov_b32_e32 v73, v66
	v_mov_b32_e32 v74, v66
	v_mov_b32_e32 v75, v66
	v_mov_b32_e32 v76, v66
	v_mov_b32_e32 v77, v66
	v_mov_b32_e32 v78, v66
	v_mov_b32_e32 v79, v66
	v_mov_b32_e32 v80, v66
	v_mov_b32_e32 v81, v66
	s_cselect_b64 vcc, -1, 0
	s_cmp_gt_i32 s61, -1
	s_waitcnt vmcnt(11)
; DI f32x16 mfma32(bf16x8 a, bf16x8 b, f32x16 c) { return __builtin_amdgcn_mfma_f32_32x32x16_bf16(a, b, c, 0, 0, 0); }
; DI float ex2(float x) { return __builtin_amdgcn_exp2f(x); }
; DI int kperm(int r) { return (r & ~12) | ((r & 4) << 1) | ((r & 8) >> 1); }
; DI void attn_A_item(const bf16_t* Q0, const bf16_t* K0, const bf16_t* VT0, const bf16_t* VTXp, const bf16_t* G, bf16_t* Y, int bh, int blk, float Mb, LAS float* Oacc, LAS float* lacc, int tid, int wave, int lane) {
;     ...
;             for (int i = 0; i < 5; ++i) {
;                 const int kt = kfirst + 32 * i, ktc = kt < 0 ? 0 : kt;
;                 load_q(kf[i], K0 + ((size_t)bh * S + (((ktc + uperm(kperm(r), seg == 1)) << sh) + res)) * 64 + 8 * h);
;             }
;             f32x16 xs[5];
; #pragma unroll
;             for (int i = 0; i < 5; ++i) {
;                 const float offs = (kfirst + 32 * i < 0) ? NEGI : mb2;
; #pragma unroll
;                 for (int e = 0; e < 16; ++e) xs[i][e] = offs;
; #pragma unroll
;                 for (int sp = 0; sp < 4; ++sp) xs[i] = mfma32(kf[i][sp], qf[sp], xs[i]);
;             }
; #pragma unroll
;             for (int i = 0; i < 5; ++i) {
;                 const int kt = kfirst + 32 * i, ktc = kt < 0 ? 0 : kt;
;                 bf16x8 vf[2][2];
;                 load_v(vf, Vs + (size_t)r * S + (size_t)res * L + ktc + 8 * h);
;                 float p[16];
; #pragma unroll
;                 for (int e = 0; e < 16; ++e) {
;                     float v = ex2(xs[i][e]);
;                     const int c = uperm(kidx(e, h), seg == 1);
;                     if ((i == 0 && c < r) || (i == 4 && c > r)) v = 0.f;
;                     p[e] = v;
;                 }
; #pragma unroll
;                 for (int e = 0; e < 16; ++e) l += p[e];
;                 pv_tile(o0, o1, vf, p);
	v_mfma_f32_32x32x16_bf16 v[66:81], v[58:61], v[18:21], v[66:81]
	v_exp_f32_e32 v82, v82
	v_exp_f32_e32 v129, v85
	v_exp_f32_e32 v85, v88
	v_exp_f32_e32 v90, v90
	v_exp_f32_e32 v91, v91
	v_exp_f32_e32 v92, v92
	v_exp_f32_e32 v93, v93
	s_waitcnt vmcnt(10)
	v_mfma_f32_32x32x16_bf16 v[66:81], v[54:57], v[22:25], v[66:81]
	v_exp_f32_e32 v88, v94
	v_exp_f32_e32 v94, v95
	v_exp_f32_e32 v95, v97
	s_mov_b32 s61, s51
	s_waitcnt vmcnt(9)
	v_mfma_f32_32x32x16_bf16 v[66:81], v[50:53], v[26:29], v[66:81]
	v_cndmask_b32_e32 v50, v195, v141, vcc
	v_mov_b32_e32 v51, v50
	v_mov_b32_e32 v52, v50
	v_mov_b32_e32 v53, v50
	v_mov_b32_e32 v54, v50
	v_mov_b32_e32 v55, v50
	v_mov_b32_e32 v56, v50
	v_mov_b32_e32 v57, v50
	v_mov_b32_e32 v58, v50
	v_mov_b32_e32 v59, v50
	v_mov_b32_e32 v60, v50
	v_mov_b32_e32 v61, v50
	v_mov_b32_e32 v62, v50
	v_mov_b32_e32 v63, v50
	v_mov_b32_e32 v64, v50
	v_mov_b32_e32 v65, v50
	s_cselect_b64 vcc, -1, 0
	s_waitcnt vmcnt(8)
	v_mfma_f32_32x32x16_bf16 v[66:81], v[34:37], v[30:33], v[66:81]
	v_cndmask_b32_e32 v34, v195, v141, vcc
	v_mov_b32_e32 v35, v34
	v_mov_b32_e32 v36, v34
	v_mov_b32_e32 v37, v34
	s_ashr_i32 s85, s84, 31
	s_lshl_b64 s[84:85], s[84:85], s93
	s_nop 5
	v_exp_f32_e32 v67, v67
	s_waitcnt vmcnt(7)
	v_mfma_f32_32x32x16_bf16 v[50:65], v[114:117], v[18:21], v[50:65]
	v_exp_f32_e32 v117, v83
	v_exp_f32_e32 v83, v84
	v_exp_f32_e32 v84, v86
	v_exp_f32_e32 v86, v87
	v_exp_f32_e32 v87, v89
	v_exp_f32_e32 v89, v96
	v_exp_f32_e32 v68, v68
	s_waitcnt vmcnt(6)
	v_mfma_f32_32x32x16_bf16 v[50:65], v[46:49], v[22:25], v[50:65]
	v_mov_b32_e32 v46, v34
	v_mov_b32_e32 v47, v34
	v_mov_b32_e32 v48, v34
	v_mov_b32_e32 v49, v34
	v_exp_f32_e32 v69, v69
	v_exp_f32_e32 v70, v70
	s_waitcnt vmcnt(5)
	v_mfma_f32_32x32x16_bf16 v[50:65], v[42:45], v[26:29], v[50:65]
	v_mov_b32_e32 v42, v34
	v_mov_b32_e32 v43, v34
	v_mov_b32_e32 v44, v34
	v_mov_b32_e32 v45, v34
	s_waitcnt vmcnt(4)
	v_mfma_f32_32x32x16_bf16 v[50:65], v[38:41], v[30:33], v[50:65]
	v_mov_b32_e32 v38, v34
	v_mov_b32_e32 v39, v34
	v_mov_b32_e32 v40, v34
	v_mov_b32_e32 v41, v34
	s_waitcnt vmcnt(3)
	s_nop 0
	v_mfma_f32_32x32x16_bf16 v[34:49], v[98:101], v[18:21], v[34:49]
	v_lshl_add_u64 v[98:99], s[84:85], 1, v[126:127]
	s_nop 3
	v_exp_f32_e32 v50, v50
	v_exp_f32_e32 v58, v58
	v_exp_f32_e32 v59, v59
	v_exp_f32_e32 v60, v60
	v_exp_f32_e32 v61, v61
	s_waitcnt vmcnt(2)
	v_mfma_f32_32x32x16_bf16 v[34:49], v[102:105], v[22:25], v[34:49]
	v_lshl_add_u64 v[22:23], s[50:51], 1, v[98:99]
	global_load_dwordx4 v[18:21], v[22:23], off
	global_load_dwordx4 v[100:103], v[22:23], off offset:32
	v_add_co_u32_e32 v22, vcc, s33, v22
	s_lshl_b32 s50, s78, 1
	s_nop 0
	v_addc_co_u32_e32 v23, vcc, 0, v23, vcc
	s_waitcnt vmcnt(3)
	v_mfma_f32_32x32x16_bf16 v[34:49], v[106:109], v[26:29], v[34:49]
	s_waitcnt vmcnt(2)
	v_mfma_f32_32x32x16_bf16 v[34:49], v[110:113], v[30:33], v[34:49]
	global_load_dwordx4 v[104:107], v[22:23], off
	global_load_dwordx4 v[108:111], v[22:23], off offset:32
	v_lshl_add_u64 v[244:245], s[64:65], 1, v[98:99]
	v_add_co_u32_e32 v246, vcc, s33, v244
	s_nop 1
	v_addc_co_u32_e32 v247, vcc, 0, v245, vcc
	global_load_dwordx4 v[196:199], v[244:245], off
	global_load_dwordx4 v[200:203], v[244:245], off offset:32
	global_load_dwordx4 v[204:207], v[246:247], off
	global_load_dwordx4 v[208:211], v[246:247], off offset:32
	v_lshl_add_u64 v[244:245], s[60:61], 1, v[98:99]
	v_add_co_u32_e32 v246, vcc, s33, v244
	s_nop 1
	v_addc_co_u32_e32 v247, vcc, 0, v245, vcc
	global_load_dwordx4 v[212:215], v[244:245], off
	global_load_dwordx4 v[216:219], v[244:245], off offset:32
	global_load_dwordx4 v[220:223], v[246:247], off
	global_load_dwordx4 v[224:227], v[246:247], off offset:32
	v_lshl_add_u64 v[244:245], s[86:87], 1, v[98:99]
	v_add_co_u32_e32 v246, vcc, s33, v244
	s_nop 1
	v_addc_co_u32_e32 v247, vcc, 0, v245, vcc
	global_load_dwordx4 v[228:231], v[244:245], off
	global_load_dwordx4 v[232:235], v[244:245], off offset:32
	global_load_dwordx4 v[236:239], v[246:247], off
	global_load_dwordx4 v[240:243], v[246:247], off offset:32
	v_cndmask_b32_e64 v22, v3, 0, s[12:13]
	v_exp_f32_e32 v3, v4
	v_exp_f32_e32 v4, v5
	v_exp_f32_e32 v5, v7
	v_exp_f32_e32 v7, v9
	v_cndmask_b32_e64 v3, v3, 0, s[14:15]
	v_cndmask_b32_e64 v23, v4, 0, s[16:17]
	v_exp_f32_e32 v4, v6
	v_cndmask_b32_e64 v6, v5, 0, s[20:21]
	v_exp_f32_e32 v5, v8
	v_exp_f32_e32 v8, v10
	v_exp_f32_e32 v10, v12
	v_exp_f32_e32 v12, v14
	v_exp_f32_e32 v14, v16
	v_add_f32_e32 v16, 0, v2
	v_add_f32_e32 v16, v22, v16
	v_add_f32_e32 v16, v3, v16
	v_cndmask_b32_e64 v4, v4, 0, s[18:19]
	v_add_f32_e32 v16, v23, v16
	v_exp_f32_e32 v9, v11
	v_add_f32_e32 v16, v4, v16
	v_cndmask_b32_e64 v5, v5, 0, s[22:23]
	v_add_f32_e32 v16, v6, v16
	v_cndmask_b32_e64 v7, v7, 0, s[24:25]
	v_exp_f32_e32 v11, v13
	v_add_f32_e32 v16, v5, v16
	v_cndmask_b32_e64 v8, v8, 0, s[26:27]
	v_add_f32_e32 v16, v7, v16
	v_cndmask_b32_e64 v9, v9, 0, s[28:29]
	v_exp_f32_e32 v13, v15
	v_add_f32_e32 v16, v8, v16
	v_cndmask_b32_e64 v10, v10, 0, s[30:31]
	v_add_f32_e32 v16, v9, v16
	v_cndmask_b32_e64 v11, v11, 0, s[34:35]
	v_exp_f32_e32 v15, v17
	v_add_f32_e32 v16, v10, v16
	v_cndmask_b32_e64 v12, v12, 0, s[36:37]
	v_add_f32_e32 v16, v11, v16
	v_cndmask_b32_e64 v13, v13, 0, s[38:39]
	v_add_f32_e32 v16, v12, v16
	v_cndmask_b32_e64 v14, v14, 0, s[40:41]
	v_add_f32_e32 v16, v13, v16
	v_cndmask_b32_e64 v15, v15, 0, s[42:43]
	v_add_f32_e32 v16, v14, v16
	v_cvt_pk_bf16_f32 v5, v5, v7
	v_cvt_pk_bf16_f32 v4, v4, v6
	v_cvt_pk_bf16_f32 v3, v3, v23
	v_cvt_pk_bf16_f32 v2, v2, v22
	v_add_f32_e32 v116, v15, v16
	v_cvt_pk_bf16_f32 v115, v14, v15
	v_cvt_pk_bf16_f32 v114, v12, v13
	v_cvt_pk_bf16_f32 v113, v10, v11
	v_cvt_pk_bf16_f32 v112, v8, v9
	s_waitcnt vmcnt(15)
; DI float ex2(float x) { return __builtin_amdgcn_exp2f(x); }
; DI void attn_A_item(const bf16_t* Q0, const bf16_t* K0, const bf16_t* VT0, const bf16_t* VTXp, const bf16_t* G, bf16_t* Y, int bh, int blk, float Mb, LAS float* Oacc, LAS float* lacc, int tid, int wave, int lane) {
;     ...
; #pragma unroll
;             for (int i = 0; i < 5; ++i) {
;                 const int kt = kfirst + 32 * i, ktc = kt < 0 ? 0 : kt;
;                 bf16x8 vf[2][2];
;                 load_v(vf, Vs + (size_t)r * S + (size_t)res * L + ktc + 8 * h);
;                 float p[16];
; #pragma unroll
;                 for (int e = 0; e < 16; ++e) {
;                     float v = ex2(xs[i][e]);
;                     const int c = uperm(kidx(e, h), seg == 1);
;                     if ((i == 0 && c < r) || (i == 4 && c > r)) v = 0.f;
;                     p[e] = v;
;                 }
; #pragma unroll
;                 for (int e = 0; e < 16; ++e) l += p[e];
;                 pv_tile(o0, o1, vf, p);
;             }
	v_mfma_f32_32x32x16_bf16 v[18:33], v[18:21], v[2:5], 0
	v_add_f32_e32 v96, v82, v116
	v_add_f32_e32 v96, v117, v96
	v_add_f32_e32 v96, v83, v96
	v_add_f32_e32 v96, v129, v96
	v_add_f32_e32 v96, v84, v96
	v_add_f32_e32 v96, v86, v96
	v_add_f32_e32 v96, v85, v96
	s_waitcnt vmcnt(13)
	v_mfma_f32_32x32x16_bf16 v[2:17], v[104:107], v[2:5], 0
	v_add_f32_e32 v96, v87, v96
	v_cvt_pk_bf16_f32 v85, v85, v87
	v_cvt_pk_bf16_f32 v84, v84, v86
	v_cvt_pk_bf16_f32 v83, v83, v129
	v_cvt_pk_bf16_f32 v82, v82, v117
	v_add_f32_e32 v96, v90, v96
	v_add_f32_e32 v96, v91, v96
	s_waitcnt vmcnt(12)
	v_mfma_f32_32x32x16_bf16 v[2:17], v[108:111], v[112:115], v[2:17]
	v_lshl_add_u64 v[108:109], s[64:65], 1, v[98:99]
	v_add_f32_e32 v96, v92, v96
	v_add_f32_e32 v96, v93, v96
	v_add_f32_e32 v96, v88, v96
	v_add_f32_e32 v96, v94, v96
	v_cvt_pk_bf16_f32 v86, v90, v91
	v_lshl_add_u64 v[90:91], s[60:61], 1, v[98:99]
	v_mfma_f32_32x32x16_bf16 v[18:33], v[100:103], v[112:115], v[18:33]
	v_add_co_u32_e32 v112, vcc, s33, v108
	v_addc_co_u32_e32 v113, vcc, 0, v109, vcc
	s_nop 0
	v_add_f32_e32 v96, v89, v96
	s_waitcnt vmcnt(11)
	v_mfma_f32_32x32x16_bf16 v[18:33], v[196:199], v[82:85], v[18:33]
	v_cvt_pk_bf16_f32 v88, v88, v94
	v_add_co_u32_e32 v94, vcc, s33, v90
	v_add_f32_e32 v116, v95, v96
	v_cvt_pk_bf16_f32 v89, v89, v95
	v_cvt_pk_bf16_f32 v87, v92, v93
	v_addc_co_u32_e32 v95, vcc, 0, v91, vcc
	s_waitcnt vmcnt(9)
	v_mfma_f32_32x32x16_bf16 v[2:17], v[204:207], v[82:85], v[2:17]
	v_exp_f32_e32 v100, v66
	v_exp_f32_e32 v101, v71
	v_exp_f32_e32 v71, v72
	v_exp_f32_e32 v72, v73
	v_add_f32_e32 v66, v100, v116
	v_add_f32_e32 v66, v67, v66
	v_add_f32_e32 v66, v68, v66
	v_mfma_f32_32x32x16_bf16 v[18:33], v[200:203], v[86:89], v[18:33]
	v_add_f32_e32 v66, v69, v66
	v_exp_f32_e32 v102, v74
	v_add_f32_e32 v66, v70, v66
	v_exp_f32_e32 v103, v75
	v_add_f32_e32 v66, v101, v66
	v_exp_f32_e32 v73, v76
	v_add_f32_e32 v66, v71, v66
	s_waitcnt vmcnt(8)
	v_mfma_f32_32x32x16_bf16 v[2:17], v[208:211], v[86:89], v[2:17]
	s_nop 0
	s_nop 0
	v_exp_f32_e32 v76, v77
	v_add_f32_e32 v66, v72, v66
	v_cvt_pk_bf16_f32 v71, v71, v72
	v_cvt_pk_bf16_f32 v70, v70, v101
	v_cvt_pk_bf16_f32 v69, v68, v69
	v_cvt_pk_bf16_f32 v68, v100, v67
	v_exp_f32_e32 v74, v78
	v_add_f32_e32 v66, v102, v66
	s_waitcnt vmcnt(7)
	v_mfma_f32_32x32x16_bf16 v[18:33], v[212:215], v[68:71], v[18:33]
	v_exp_f32_e32 v77, v79
	v_add_f32_e32 v66, v103, v66
	v_add_f32_e32 v66, v73, v66
	v_exp_f32_e32 v75, v80
	v_exp_f32_e32 v78, v81
	v_add_f32_e32 v66, v76, v66
	v_add_f32_e32 v66, v74, v66
	s_waitcnt vmcnt(5)
	v_mfma_f32_32x32x16_bf16 v[2:17], v[220:223], v[68:71], v[2:17]
	v_add_f32_e32 v66, v77, v66
	v_cvt_pk_bf16_f32 v74, v74, v77
	v_cvt_pk_bf16_f32 v73, v73, v76
	v_lshl_add_u64 v[76:77], s[86:87], 1, v[98:99]
	v_add_co_u32_e32 v80, vcc, s33, v76
	v_add_f32_e32 v66, v75, v66
	v_cvt_pk_bf16_f32 v75, v75, v78
	v_cvt_pk_bf16_f32 v72, v102, v103
	v_addc_co_u32_e32 v81, vcc, 0, v77, vcc
	v_add_f32_e32 v66, v78, v66
	v_mfma_f32_32x32x16_bf16 v[18:33], v[216:219], v[72:75], v[18:33]
	v_exp_f32_e32 v67, v51
	v_exp_f32_e32 v51, v52
	v_exp_f32_e32 v84, v53
	v_exp_f32_e32 v52, v54
	v_exp_f32_e32 v54, v55
	v_exp_f32_e32 v55, v57
	v_exp_f32_e32 v57, v64
	s_waitcnt vmcnt(4)
	v_mfma_f32_32x32x16_bf16 v[2:17], v[224:227], v[72:75], v[2:17]
	s_nop 0
	s_nop 0
	v_add_f32_e32 v64, v50, v66
	v_add_f32_e32 v64, v67, v64
	v_exp_f32_e32 v53, v56
	v_add_f32_e32 v64, v51, v64
	v_add_f32_e32 v64, v84, v64
	v_add_f32_e32 v64, v52, v64
	v_add_f32_e32 v64, v54, v64
	v_add_f32_e32 v64, v53, v64
	v_add_f32_e32 v64, v55, v64
	v_exp_f32_e32 v56, v62
	v_add_f32_e32 v64, v58, v64
	v_exp_f32_e32 v62, v63
	v_add_f32_e32 v64, v59, v64
	v_cvt_pk_bf16_f32 v53, v53, v55
	v_cvt_pk_bf16_f32 v52, v52, v54
	v_cvt_pk_bf16_f32 v51, v51, v84
	v_cvt_pk_bf16_f32 v50, v50, v67
	v_add_f32_e32 v64, v60, v64
	v_exp_f32_e32 v63, v65
	s_waitcnt vmcnt(3)
	v_mfma_f32_32x32x16_bf16 v[18:33], v[228:231], v[50:53], v[18:33]
	v_add_f32_e32 v64, v61, v64
	v_add_f32_e32 v64, v56, v64
	v_add_f32_e32 v64, v62, v64
	v_add_f32_e32 v64, v57, v64
	v_add_f32_e32 v66, v63, v64
	v_cvt_pk_bf16_f32 v57, v57, v63
	v_cvt_pk_bf16_f32 v56, v56, v62
	s_waitcnt vmcnt(1)
; #define LAS __attribute__((address_space(3)))
; template <int O> DI float shx(float v) { return __builtin_bit_cast(float, shxi<O>(__builtin_bit_cast(int, v))); }
; DI float ex2(float x) { return __builtin_amdgcn_exp2f(x); }
; DI void attn_A_item(const bf16_t* Q0, const bf16_t* K0, const bf16_t* VT0, const bf16_t* VTXp, const bf16_t* G, bf16_t* Y, int bh, int blk, float Mb, LAS float* Oacc, LAS float* lacc, int tid, int wave, int lane) {
;     ...
; #pragma unroll
;             for (int i = 0; i < 5; ++i) {
;                 const int kt = kfirst + 32 * i, ktc = kt < 0 ? 0 : kt;
;                 bf16x8 vf[2][2];
;                 load_v(vf, Vs + (size_t)r * S + (size_t)res * L + ktc + 8 * h);
;                 float p[16];
; #pragma unroll
;                 for (int e = 0; e < 16; ++e) {
;                     float v = ex2(xs[i][e]);
;                     const int c = uperm(kidx(e, h), seg == 1);
;                     if ((i == 0 && c < r) || (i == 4 && c > r)) v = 0.f;
;                     p[e] = v;
;                 }
; #pragma unroll
;                 for (int e = 0; e < 16; ++e) l += p[e];
;                 pv_tile(o0, o1, vf, p);
;             }
;             l += shx<32>(l);
;             const int tl = t - t0;
; #pragma unroll
;             for (int dd = 0; dd < 2; ++dd)
; #pragma unroll
;                 for (int g = 0; g < 4; ++g) {
;                     LAS f32x4* pp = (LAS f32x4*)(Oacc + tl * 68 + 32 * dd + 8 * g + 4 * h);
;                     f32x4 cur = *pp;
; #pragma unroll
;                     for (int e = 0; e < 4; ++e) cur[e] += (dd == 0 ? o0[4 * g + e] : o1[4 * g + e]);
;                     *pp = cur;
;                 }
;             if (h == 0) lacc[tl] += l;
	v_mfma_f32_32x32x16_bf16 v[2:17], v[236:239], v[50:53], v[2:17]
	v_lshl_add_u64 v[50:51], v[98:99], 0, s[50:51]
	v_cvt_pk_bf16_f32 v55, v60, v61
	v_cvt_pk_bf16_f32 v54, v58, v59
	global_load_dwordx4 v[62:65], v[50:51], off
	global_load_dwordx4 v[58:61], v[50:51], off offset:32
	v_add_co_u32_e32 v50, vcc, s33, v50
	v_exp_f32_e32 v36, v36
	s_nop 0
	v_addc_co_u32_e32 v51, vcc, 0, v51, vcc
	v_mfma_f32_32x32x16_bf16 v[18:33], v[232:235], v[54:57], v[18:33]
	v_cndmask_b32_e64 v67, v36, 0, s[48:49]
	v_exp_f32_e32 v36, v37
	v_exp_f32_e32 v34, v34
	v_exp_f32_e32 v35, v35
	v_cndmask_b32_e64 v37, v36, 0, s[90:91]
	v_exp_f32_e32 v36, v38
	s_waitcnt vmcnt(2)
	v_mfma_f32_32x32x16_bf16 v[2:17], v[240:243], v[54:57], v[2:17]
	global_load_dwordx4 v[54:57], v[50:51], off
	s_nop 0
	global_load_dwordx4 v[50:53], v[50:51], off offset:32
	v_cndmask_b32_e64 v34, v34, 0, s[44:45]
	v_cndmask_b32_e64 v38, v36, 0, s[52:53]
	v_exp_f32_e32 v36, v39
	v_cndmask_b32_e64 v35, v35, 0, s[46:47]
	v_cndmask_b32_e64 v39, v36, 0, s[54:55]
	v_exp_f32_e32 v36, v40
	s_nop 0
	v_cndmask_b32_e64 v40, v36, 0, s[56:57]
	v_exp_f32_e32 v36, v41
	s_nop 0
	v_cndmask_b32_e64 v41, v36, 0, s[58:59]
	v_exp_f32_e32 v36, v42
	s_nop 0
	v_cndmask_b32_e64 v42, v36, 0, s[76:77]
	v_exp_f32_e32 v36, v43
	s_nop 0
	v_cndmask_b32_e64 v68, v36, 0, s[62:63]
	v_exp_f32_e32 v36, v44
	s_nop 0
	v_cndmask_b32_e64 v43, v36, 0, s[2:3]
	v_exp_f32_e32 v36, v45
	s_nop 0
	v_cndmask_b32_e64 v69, v36, 0, s[66:67]
	v_exp_f32_e32 v36, v46
	s_nop 0
	v_cndmask_b32_e64 v44, v36, 0, s[68:69]
	v_exp_f32_e32 v36, v47
	s_nop 0
	v_cndmask_b32_e64 v46, v36, 0, s[70:71]
	v_exp_f32_e32 v36, v48
	s_nop 0
	v_cndmask_b32_e64 v45, v36, 0, s[72:73]
	v_exp_f32_e32 v36, v49
	s_nop 0
	v_cndmask_b32_e64 v47, v36, 0, s[74:75]
	v_add_f32_e32 v36, v34, v66
	v_add_f32_e32 v36, v35, v36
	v_add_f32_e32 v36, v67, v36
	v_add_f32_e32 v36, v37, v36
	v_add_f32_e32 v36, v38, v36
	v_add_f32_e32 v36, v39, v36
	v_add_f32_e32 v36, v40, v36
	v_add_f32_e32 v36, v41, v36
	v_cvt_pk_bf16_f32 v41, v40, v41
	v_cvt_pk_bf16_f32 v40, v38, v39
	v_cvt_pk_bf16_f32 v39, v67, v37
	v_cvt_pk_bf16_f32 v38, v34, v35
	v_add_f32_e32 v36, v42, v36
	v_add_f32_e32 v36, v68, v36
	s_waitcnt vmcnt(3)
	v_mfma_f32_32x32x16_bf16 v[18:33], v[62:65], v[38:41], v[18:33]
	v_add_f32_e32 v36, v43, v36
	v_add_f32_e32 v36, v69, v36
	v_add_f32_e32 v36, v44, v36
	v_add_f32_e32 v36, v46, v36
	v_add_f32_e32 v36, v45, v36
	v_cvt_pk_bf16_f32 v45, v45, v47
	v_cvt_pk_bf16_f32 v44, v44, v46
	s_waitcnt vmcnt(1)
	v_mfma_f32_32x32x16_bf16 v[2:17], v[54:57], v[38:41], v[2:17]
	v_cvt_pk_bf16_f32 v43, v43, v69
	v_cvt_pk_bf16_f32 v42, v42, v68
	v_subrev_u32_e32 v39, s81, v128
	v_mad_u64_u32 v[34:35], s[60:61], v39, s79, v[124:125]
	v_add_f32_e32 v36, v47, v36
	v_mov_b32_e32 v37, v36
	v_mfma_f32_32x32x16_bf16 v[18:33], v[58:61], v[42:45], v[18:33]
	v_mov_b32_e32 v38, v36
	s_nop 1
	v_permlane32_swap_b32_e32 v37, v38
	s_waitcnt vmcnt(0)
	v_mfma_f32_32x32x16_bf16 v[2:17], v[50:53], v[42:45], v[2:17]
	ds_read_b128 v[40:43], v34
	s_waitcnt lgkmcnt(0)
	s_nop 3
	v_add_f32_e64 v18, v18, v40
	v_add_f32_e64 v19, v19, v41
	v_add_f32_e64 v20, v20, v42
	v_add_f32_e64 v21, v21, v43
	ds_write_b128 v34, v[18:21]
	ds_read_b128 v[18:21], v34 offset:32
	ds_read_b128 v[40:43], v34 offset:64
	s_waitcnt lgkmcnt(1)
	v_pk_add_f32 v[18:19], v[22:23], v[18:19]
	v_pk_add_f32 v[20:21], v[24:25], v[20:21]
	ds_write_b128 v34, v[18:21] offset:32
	s_waitcnt lgkmcnt(1)
	v_pk_add_f32 v[18:19], v[26:27], v[40:41]
	v_pk_add_f32 v[20:21], v[28:29], v[42:43]
	ds_write_b128 v34, v[18:21] offset:64
	ds_read_b128 v[18:21], v34 offset:96
	s_waitcnt lgkmcnt(0)
	v_pk_add_f32 v[18:19], v[30:31], v[18:19]
	v_pk_add_f32 v[20:21], v[32:33], v[20:21]
	ds_write_b128 v34, v[18:21] offset:96
	ds_read_b128 v[18:21], v34 offset:128
	s_waitcnt lgkmcnt(0)
	v_pk_add_f32 v[2:3], v[2:3], v[18:19]
	v_pk_add_f32 v[4:5], v[4:5], v[20:21]
	ds_write_b128 v34, v[2:5] offset:128
	ds_read_b128 v[2:5], v34 offset:160
	s_waitcnt lgkmcnt(0)
	v_pk_add_f32 v[2:3], v[6:7], v[2:3]
	v_pk_add_f32 v[4:5], v[8:9], v[4:5]
	ds_write_b128 v34, v[2:5] offset:160
	ds_read_b128 v[2:5], v34 offset:192
	s_waitcnt lgkmcnt(0)
	v_pk_add_f32 v[2:3], v[10:11], v[2:3]
	v_pk_add_f32 v[4:5], v[12:13], v[4:5]
	ds_write_b128 v34, v[2:5] offset:192
	ds_read_b128 v[2:5], v34 offset:224
	s_waitcnt lgkmcnt(0)
	v_pk_add_f32 v[2:3], v[14:15], v[2:3]
	v_pk_add_f32 v[4:5], v[16:17], v[4:5]
	ds_write_b128 v34, v[2:5] offset:224
	s_and_saveexec_b64 s[60:61], s[8:9]
	s_cbranch_execz .LBB0_304
	v_lshl_add_u32 v2, v39, 2, 0
	v_add_u32_e32 v2, 0x22000, v2
	ds_read_b32 v4, v2
	v_cndmask_b32_e64 v3, v37, v38, s[6:7]
	v_add_f32_e32 v3, v36, v3
	s_waitcnt lgkmcnt(0)
	v_add_f32_e32 v3, v3, v4
	ds_write_b32 v2, v3
	s_branch .LBB0_304

; #define LAS __attribute__((address_space(3)))
; DI int kperm(int r) { return (r & ~12) | ((r & 4) << 1) | ((r & 8) >> 1); }
; DI void attn_wgB_item(const bf16_t* Qm, const bf16_t* Km, const bf16_t* Vtm, const bf16_t* G, bf16_t* Y, int bh, int qb2, int halfq, LAS unsigned char* lds, int tid, int wave, int lane) {
;     asm volatile("" : "+v"(tid), "+v"(lane));
;     const int r = lane & 31, h = lane >> 5;
;     const int qtA = halfq ? qb2 * 8 + wave : qb2 * 16 + wave, qtB = halfq ? -1 : qb2 * 16 + 15 - wave, tA = qtA * 32 + r, tB = halfq ? tA : qtB * 32 + r;
;     bf16x8 qfA[4], qfB[4];
;     load_q(qfA, Qm + ((size_t)bh * S + tA) * 64 + 8 * h);
;     load_q(qfB, Qm + ((size_t)bh * S + tB) * 64 + 8 * h);
;     f32x16 oA0, oA1, oB0, oB1;
; #pragma unroll
;     for (int i = 0; i < 16; ++i) { oA0[i] = 0.f; oA1[i] = 0.f; oB0[i] = 0.f; oB1[i] = 0.f; }
;     float RA = 0.f, RB = 0.f;
;     bool doneA = false, doneB = (halfq != 0);
;     const int srow = tid >> 3, sch = tid & 7;
;     const bf16_t* kg = Km + ((size_t)bh * S + srow) * 64 + sch * 8;
;     const bf16_t* vg = Vtm + ((size_t)bh * 64 + srow) * S + sch * 8;
;     const unsigned kws = AW_K + srow * 144 + sch * 16, vws = AW_V + srow * 144 + sch * 16;
;     const unsigned kra = AW_K + kperm(r) * 144 + 16 * h, vra = AW_V + r * 144 + 16 * h;
;     LAS int* fl = (LAS int*)(lds + 2 * AW_BUF);
;     int cur = halfq ? qb2 * 4 + 3 : qb2 * 8 + 7, buf = 0, it = 0;
;     {
;         const bf16x8 kreg = *(const bf16x8*)(kg + (size_t)cur * 4096);
;         const u32x4 vreg = *(const u32x4*)(vg + cur * 64);
;         *(LAS bf16x8*)(lds + kws) = kreg;
;         *(LAS u32x4*)(lds + vws) = vreg;
;     }
;     __syncthreads();
; __global__ void __launch_bounds__(512, 2) mega_fwd(Args a) {
;     ...
;                         if (tid == 0) *qw = (int)atomicAdd(ctr, 1u);
;                         __syncthreads();
;                         const int idx = __builtin_amdgcn_readfirstlane(*qw);
;                         __syncthreads();
;                         if (idx >= 64) break;
;                         const int qb = 31 - (idx >> 1), bh = 2 * q + (idx & 1);
;                         attn_wgB_item(Qb + (size_t)1 * 16 * S * 64, Kb + (size_t)1 * 16 * S * 64, VT + (size_t)1 * 16 * 64 * S, Gb, Yb, bh, qb, 1, lds, tid, wave, lane);
.LBB0_431:
	s_or_b64 exec, exec, s[2:3]
	v_mov_b32_e32 v0, s86
	s_waitcnt lgkmcnt(0)
	s_barrier
	ds_read_b32 v0, v0
	s_mov_b64 s[2:3], -1
	s_waitcnt lgkmcnt(0)
	s_barrier
	v_readfirstlane_b32 s10, v0
	s_cmp_gt_i32 s10, 63
	s_cbranch_scc1 .LBB0_426
	s_and_b32 s2, s10, 1
	v_mov_b32_e32 v0, v165
	v_mov_b32_e32 v14, v178
	s_ashr_i32 s54, s10, 1
	s_or_b32 s64, s2, s63
	s_sub_i32 s11, 31, s54
	v_ashrrev_i32_e32 v12, 3, v0
	s_lshl_b32 s50, s64, 13
	v_ashrrev_i32_e32 v13, 31, v12
	s_lshl_b32 s65, s11, 3
	v_readlane_b32 s2, v254, 44
	v_lshl_add_u64 v[2:3], s[50:51], 0, v[12:13]
	v_and_b32_e32 v15, 31, v14
	s_add_i32 s65, s65, s2
	v_lshlrev_b64 v[2:3], 7, v[2:3]
	v_lshlrev_b32_e32 v0, 4, v0
	s_lshl_b32 s2, s64, 20
	v_lshl_or_b32 v108, s65, 5, v15
	v_lshl_add_u64 v[2:3], s[4:5], 0, v[2:3]
	v_and_b32_e32 v0, 0x70, v0
	s_add_u32 s2, s58, s2
	v_ashrrev_i32_e32 v109, 31, v108
	v_lshl_add_u64 v[110:111], v[2:3], 0, v[0:1]
	s_addc_u32 s3, s59, 0
	v_lshlrev_b64 v[2:3], 14, v[12:13]
	v_lshl_add_u64 v[10:11], s[50:51], 0, v[108:109]
	v_lshl_add_u64 v[2:3], s[2:3], 0, v[2:3]
	s_lshl_b32 s2, s11, 2
	v_ashrrev_i32_e32 v13, 5, v14
	s_or_b32 s50, s2, 3
	v_lshlrev_b32_e32 v106, 3, v13
	v_lshlrev_b64 v[10:11], 7, v[10:11]
	v_lshl_add_u64 v[112:113], v[2:3], 0, v[0:1]
	s_lshl_b64 s[2:3], s[50:51], 13
	s_lshl_b32 s50, s50, 6
	v_ashrrev_i32_e32 v107, 31, v106
	v_lshl_add_u64 v[10:11], s[0:1], 0, v[10:11]
	v_lshl_add_u64 v[2:3], v[110:111], 0, s[2:3]
	v_lshl_add_u64 v[6:7], s[50:51], 1, v[112:113]
	v_lshl_add_u64 v[10:11], v[106:107], 1, v[10:11]
	global_load_dwordx4 v[2:5], v[2:3], off
	s_nop 0
	global_load_dwordx4 v[6:9], v[6:7], off
	s_nop 0
	global_load_dwordx4 v[64:67], v[10:11], off
	global_load_dwordx4 v[68:71], v[10:11], off offset:32
	global_load_dwordx4 v[72:75], v[10:11], off offset:64
	global_load_dwordx4 v[76:79], v[10:11], off offset:96
	v_lshlrev_b32_e32 v11, 1, v14
	v_lshrrev_b32_e32 v16, 1, v14
	v_mul_lo_u32 v12, v12, s91
	v_and_b32_e32 v10, 19, v14
	v_and_b32_e32 v11, 8, v11
	v_and_b32_e32 v16, 4, v16
	v_add3_u32 v117, v12, v0, 0
	v_or_b32_e32 v0, 1, v106
	v_lshlrev_b32_e32 v105, 4, v13
	v_or3_b32 v10, v10, v11, v16
	v_or_b32_e32 v11, 2, v106
	v_or_b32_e32 v12, 3, v106
	v_or_b32_e32 v13, 4, v106
	v_or_b32_e32 v16, 5, v106
	v_or_b32_e32 v17, 6, v106
	v_or_b32_e32 v18, 7, v106
	v_add_u32_e32 v104, 16, v106
	v_add_u32_e32 v19, 17, v106
	v_add_u32_e32 v20, 18, v106
	v_add_u32_e32 v21, 19, v106
	v_add_u32_e32 v22, 20, v106
	v_add_u32_e32 v23, 21, v106
	v_add_u32_e32 v24, 22, v106
	v_cmp_lt_i32_e64 s[12:13], v0, v15
	v_add_u32_e32 v0, 23, v106
	s_lshl_b32 s2, s54, 2
	v_mul_u32_u24_e32 v116, 0x90, v15
	v_cmp_lt_i32_e64 s[10:11], v106, v15
	v_cmp_lt_i32_e64 s[14:15], v11, v15
	v_cmp_lt_i32_e64 s[16:17], v12, v15
	v_cmp_lt_i32_e64 s[18:19], v13, v15
	v_cmp_lt_i32_e64 s[20:21], v16, v15
	v_cmp_lt_i32_e64 s[22:23], v17, v15
	v_cmp_lt_i32_e64 s[24:25], v18, v15
	v_cmp_lt_i32_e64 s[26:27], v104, v15
	v_cmp_lt_i32_e64 s[28:29], v19, v15
	v_cmp_lt_i32_e64 s[30:31], v20, v15
	v_cmp_lt_i32_e64 s[34:35], v21, v15
	v_cmp_lt_i32_e64 s[36:37], v22, v15
	v_cmp_lt_i32_e64 s[38:39], v23, v15
	v_cmp_lt_i32_e64 s[40:41], v24, v15
	v_cmp_lt_i32_e64 s[42:43], v0, v15
	v_cmp_gt_u32_e64 s[44:45], 32, v14
	v_cmp_eq_u32_e64 s[46:47], 0, v14
	s_sub_i32 s50, 0x7e, s2
	s_lshl_b32 s2, s54, 3
	v_mov_b32_e32 v14, v1
	v_mov_b32_e32 v15, v1
	v_mul_u32_u24_e32 v118, 0x90, v10
	s_waitcnt vmcnt(5)
	ds_write_b128 v117, v[2:5]
	s_waitcnt vmcnt(4)
	ds_write_b128 v117, v[6:9] offset:9216
	s_sub_i32 s67, 0xfe, s2
	s_lshl_b32 s2, s54, 8
	v_mov_b32_e32 v0, v1
	v_mov_b32_e32 v2, v1
	v_mov_b32_e32 v3, v1
	v_mov_b32_e32 v4, v1
	v_mov_b32_e32 v5, v1
	v_mov_b32_e32 v6, v1
	v_mov_b32_e32 v7, v1
	v_mov_b32_e32 v8, v1
	v_mov_b32_e32 v9, v1
	v_mov_b32_e32 v10, v1
	v_mov_b32_e32 v11, v1
	v_mov_b32_e32 v12, v1
	v_mov_b32_e32 v13, v1
	v_mov_b64_e32 v[30:31], v[14:15]
	v_mov_b64_e32 v[46:47], v[14:15]
	s_mov_b32 s66, 0
	s_sub_i32 s2, 0x1f80, s2
	v_mov_b32_e32 v119, 0
	s_mov_b64 s[56:57], 0
	s_mov_b32 s68, s61
	s_mov_b32 s69, 0
	v_mov_b64_e32 v[28:29], v[12:13]
	v_mov_b64_e32 v[26:27], v[10:11]
	v_mov_b64_e32 v[24:25], v[8:9]
	v_mov_b64_e32 v[22:23], v[6:7]
	v_mov_b64_e32 v[20:21], v[4:5]
	v_mov_b64_e32 v[18:19], v[2:3]
	v_mov_b64_e32 v[16:17], v[0:1]
	v_mov_b64_e32 v[44:45], v[12:13]
	v_mov_b64_e32 v[42:43], v[10:11]
	v_mov_b64_e32 v[40:41], v[8:9]
	v_mov_b64_e32 v[38:39], v[6:7]
	v_mov_b64_e32 v[36:37], v[4:5]
	v_mov_b64_e32 v[34:35], v[2:3]
	v_mov_b64_e32 v[32:33], v[0:1]
	s_waitcnt vmcnt(0) lgkmcnt(0)
	s_barrier
	s_branch .LBB0_434

; #define LAS __attribute__((address_space(3)))
; DI float ex2(float x) { return __builtin_amdgcn_exp2f(x); }
; DI float lg2(float x) { return __builtin_amdgcn_logf(x); }
; DI void sub_tile_sb(const bf16x8 (&kf)[4], const bf16x8 (&vf)[2][2], const bf16x8 (&qf)[4], f32x16& o0, f32x16& o1, float& R, bool diag, int r, int h) {
;     const f32x16 x = qk_tile(kf, qf);
;     float sp_[16], p[16];
; #pragma unroll
;     for (int e = 0; e < 16; ++e) { const float z = x[e]; sp_[e] = fmaxf(z, 0.f) + LN2 * lg2(1.0f + ex2(-fabsf(z) * LOG2E)); }
;     if (diag) {
; #pragma unroll
;         for (int e = 0; e < 16; ++e) if (!(kidx(e, h) < r)) sp_[e] = 0.f;
; DI void attn_wgB_item(const bf16_t* Qm, const bf16_t* Km, const bf16_t* Vtm, const bf16_t* G, bf16_t* Y, int bh, int qb2, int halfq, LAS unsigned char* lds, int tid, int wave, int lane) {
;     ...
;             const int tau = cur * 2 + kk;
;             const bool actA = (tau <= qtA) && !doneA, actB = (tau <= qtB) && !doneB;
;             if (actA || actB) {
;                 bf16x8 kf[4], vf[2][2];
; #pragma unroll
;                 for (int sp = 0; sp < 4; ++sp) kf[sp] = *(LAS bf16x8*)(lb + kra + kk * 32 * 144 + sp * 32);
; #pragma unroll
;                 for (int dd = 0; dd < 2; ++dd)
; #pragma unroll
;                     for (int s = 0; s < 2; ++s) vf[dd][s] = *(LAS bf16x8*)(lb + vra + dd * 32 * 144 + kk * 64 + s * 32);
;                 if (actA) { sub_tile_sb(kf, vf, qfA, oA0, oA1, RA, tau == qtA, r, h); if (__ballot(RA < 104.0f) == 0ull) doneA = true; }
.LBB0_437:
	s_mul_i32 s3, s69, 0x4900
	s_add_i32 s3, s3, 0
	s_cmp_ge_i32 s67, s65
	s_cselect_b64 s[72:73], -1, 0
	v_add_u32_e32 v0, s3, v118
	v_add_u32_e32 v2, s3, v116
	s_or_b64 s[72:73], s[72:73], s[56:57]
	s_and_b64 vcc, exec, s[72:73]
	v_add_u32_e32 v121, v0, v105
	v_add_u32_e32 v120, v2, v105
	s_cbranch_vccnz .LBB0_443
	ds_read_b128 v[2:5], v121 offset:4608
	ds_read_b128 v[6:9], v121 offset:4640
	s_cmp_eq_u32 s68, 0
	s_cselect_b64 s[56:57], -1, 0
	s_cmp_lg_u32 s68, 0
	s_waitcnt lgkmcnt(1)
	v_mfma_f32_32x32x16_bf16 v[48:63], v[2:5], v[64:67], 0
	s_waitcnt lgkmcnt(0)
	v_mfma_f32_32x32x16_bf16 v[48:63], v[6:9], v[68:71], v[48:63]
	ds_read_b128 v[2:5], v121 offset:4672
	ds_read_b128 v[6:9], v121 offset:4704
	ds_read_b128 v[100:103], v120 offset:9280
	ds_read_b128 v[96:99], v120 offset:9312
	ds_read_b128 v[92:95], v120 offset:13888
	ds_read_b128 v[88:91], v120 offset:13920
	s_waitcnt lgkmcnt(5)
	v_mfma_f32_32x32x16_bf16 v[48:63], v[2:5], v[72:75], v[48:63]
	s_waitcnt lgkmcnt(4)
	v_mfma_f32_32x32x16_bf16 v[48:63], v[6:9], v[76:79], v[48:63]
	s_nop 11
	v_max_f32_e32 v0, v48, v48
	v_mul_f32_e64 v2, |v48|, s99
	v_mul_f32_e64 v4, |v49|, s99
	v_max_f32_e32 v14, 0, v0
	v_exp_f32_e32 v0, v2
	v_exp_f32_e32 v2, v4
	v_max_f32_e32 v3, v49, v49
	v_mul_f32_e64 v6, |v50|, s99
	v_mul_f32_e64 v115, |v53|, s99
	v_max_f32_e32 v15, 0, v3
	v_exp_f32_e32 v3, v6
	v_exp_f32_e32 v6, v115
	v_add_f32_e32 v2, 1.0, v2
	v_log_f32_e32 v123, v2
	v_mul_f32_e64 v2, |v54|, s99
	v_exp_f32_e32 v2, v2
	v_add_f32_e32 v0, 1.0, v0
	v_log_f32_e32 v122, v0
	v_add_f32_e32 v0, 1.0, v6
	v_mul_f32_e64 v8, |v51|, s99
	v_log_f32_e32 v127, v0
	v_max_f32_e32 v0, v54, v54
	v_exp_f32_e32 v4, v8
	v_max_f32_e32 v8, 0, v0
	v_add_f32_e32 v0, 1.0, v2
	v_mul_f32_e64 v2, |v55|, s99
	v_exp_f32_e32 v2, v2
	v_max_f32_e32 v9, v52, v52
	v_log_f32_e32 v128, v0
	v_max_f32_e32 v0, v55, v55
	v_max_f32_e32 v10, 0, v9
	v_max_f32_e32 v9, 0, v0
	v_add_f32_e32 v0, 1.0, v2
	v_mul_f32_e64 v2, |v56|, s99
	v_exp_f32_e32 v2, v2
	v_log_f32_e32 v129, v0
	v_max_f32_e32 v0, v56, v56
	v_max_f32_e32 v6, 0, v0
	v_add_f32_e32 v0, 1.0, v2
	v_mul_f32_e64 v2, |v57|, s99
	v_exp_f32_e32 v2, v2
	v_max_f32_e32 v7, v51, v51
	v_log_f32_e32 v130, v0
	v_max_f32_e32 v0, v57, v57
	v_max_f32_e32 v13, 0, v7
	v_max_f32_e32 v7, 0, v0
	v_add_f32_e32 v0, 1.0, v2
	v_mul_f32_e64 v2, |v58|, s99
	v_exp_f32_e32 v2, v2
	v_max_f32_e32 v5, v50, v50
	v_mul_f32_e64 v11, |v52|, s99
	v_add_f32_e32 v4, 1.0, v4
	v_log_f32_e32 v131, v0
	v_max_f32_e32 v0, v58, v58
	v_max_f32_e32 v12, 0, v5
	v_exp_f32_e32 v5, v11
	v_log_f32_e32 v125, v4
	v_max_f32_e32 v4, 0, v0
	v_add_f32_e32 v0, 1.0, v2
	v_mul_f32_e64 v2, |v59|, s99
	v_exp_f32_e32 v2, v2
	v_add_f32_e32 v5, 1.0, v5
	v_log_f32_e32 v132, v0
	v_max_f32_e32 v0, v59, v59
	v_add_f32_e32 v3, 1.0, v3
	v_log_f32_e32 v126, v5
	v_max_f32_e32 v5, 0, v0
	v_add_f32_e32 v0, 1.0, v2
	v_mul_f32_e64 v2, |v60|, s99
	v_log_f32_e32 v124, v3
	v_exp_f32_e32 v3, v2
	v_log_f32_e32 v133, v0
	v_max_f32_e32 v0, v60, v60
	v_max_f32_e32 v114, v53, v53
	v_max_f32_e32 v2, 0, v0
	v_add_f32_e32 v0, 1.0, v3
	v_mul_f32_e64 v3, |v61|, s99
	v_max_f32_e32 v11, 0, v114
	v_exp_f32_e32 v114, v3
	v_log_f32_e32 v134, v0
	v_max_f32_e32 v0, v61, v61
	v_max_f32_e32 v3, 0, v0
	v_add_f32_e32 v0, 1.0, v114
	v_log_f32_e32 v135, v0
	v_mul_f32_e64 v0, |v62|, s99
	v_exp_f32_e32 v0, v0
	v_mul_f32_e64 v114, |v63|, s99
	v_exp_f32_e32 v115, v114
	v_max_f32_e32 v136, v62, v62
	v_add_f32_e32 v0, 1.0, v0
	v_log_f32_e32 v114, v0
	v_add_f32_e32 v0, 1.0, v115
	v_log_f32_e32 v115, v0
	v_max_f32_e32 v0, v63, v63
	v_max_f32_e32 v136, 0, v136
	v_max_f32_e32 v137, 0, v0
	v_pk_fma_f32 v[114:115], v[114:115], s[96:97], v[136:137] op_sel_hi:[1,0,1]
	v_pk_fma_f32 v[2:3], v[134:135], s[96:97], v[2:3] op_sel_hi:[1,0,1]
	v_pk_fma_f32 v[4:5], v[132:133], s[96:97], v[4:5] op_sel_hi:[1,0,1]
	v_pk_fma_f32 v[6:7], v[130:131], s[96:97], v[6:7] op_sel_hi:[1,0,1]
	v_pk_fma_f32 v[8:9], v[128:129], s[96:97], v[8:9] op_sel_hi:[1,0,1]
	v_pk_fma_f32 v[10:11], v[126:127], s[96:97], v[10:11] op_sel_hi:[1,0,1]
	v_pk_fma_f32 v[12:13], v[124:125], s[96:97], v[12:13] op_sel_hi:[1,0,1]
	v_pk_fma_f32 v[14:15], v[122:123], s[96:97], v[14:15] op_sel_hi:[1,0,1]
	s_cbranch_scc1 .LBB0_440
	s_or_b64 vcc, s[42:43], s[40:41]
	v_cndmask_b32_e32 v114, 0, v114, vcc
	s_or_b64 vcc, vcc, s[38:39]
	v_cndmask_b32_e32 v3, 0, v3, vcc
	s_or_b64 vcc, vcc, s[36:37]
	v_cndmask_b32_e32 v2, 0, v2, vcc
	s_or_b64 vcc, vcc, s[34:35]
	v_cndmask_b32_e32 v5, 0, v5, vcc
	s_or_b64 vcc, vcc, s[30:31]
	v_cndmask_b32_e32 v4, 0, v4, vcc
	s_or_b64 vcc, vcc, s[28:29]
	v_cndmask_b32_e32 v7, 0, v7, vcc
	s_or_b64 vcc, vcc, s[26:27]
	v_cndmask_b32_e32 v6, 0, v6, vcc
	s_or_b64 vcc, vcc, s[24:25]
	v_cndmask_b32_e32 v9, 0, v9, vcc
	s_or_b64 vcc, vcc, s[22:23]
	v_cndmask_b32_e32 v8, 0, v8, vcc
	s_or_b64 vcc, vcc, s[20:21]
	v_cndmask_b32_e32 v11, 0, v11, vcc
	s_or_b64 vcc, vcc, s[18:19]
	v_cndmask_b32_e32 v10, 0, v10, vcc
	s_or_b64 vcc, vcc, s[16:17]
	v_cndmask_b32_e32 v13, 0, v13, vcc
	s_or_b64 vcc, vcc, s[14:15]
	v_cndmask_b32_e32 v12, 0, v12, vcc
	s_or_b64 vcc, vcc, s[12:13]
	v_cndmask_b32_e32 v15, 0, v15, vcc
	s_or_b64 vcc, vcc, s[10:11]
	v_cndmask_b32_e64 v115, 0, v115, s[42:43]
	v_cndmask_b32_e32 v14, 0, v14, vcc

; #define LAS __attribute__((address_space(3)))
; DI float ex2(float x) { return __builtin_amdgcn_exp2f(x); }
; DI float lg2(float x) { return __builtin_amdgcn_logf(x); }
; DI void sub_tile_sb(const bf16x8 (&kf)[4], const bf16x8 (&vf)[2][2], const bf16x8 (&qf)[4], f32x16& o0, f32x16& o1, float& R, bool diag, int r, int h) {
;     const f32x16 x = qk_tile(kf, qf);
;     float sp_[16], p[16];
; #pragma unroll
;     for (int e = 0; e < 16; ++e) { const float z = x[e]; sp_[e] = fmaxf(z, 0.f) + LN2 * lg2(1.0f + ex2(-fabsf(z) * LOG2E)); }
;     if (diag) {
; #pragma unroll
;         for (int e = 0; e < 16; ++e) if (!(kidx(e, h) < r)) sp_[e] = 0.f;
; DI void attn_wgB_item(const bf16_t* Qm, const bf16_t* Km, const bf16_t* Vtm, const bf16_t* G, bf16_t* Y, int bh, int qb2, int halfq, LAS unsigned char* lds, int tid, int wave, int lane) {
;     ...
;             const int tau = cur * 2 + kk;
;             const bool actA = (tau <= qtA) && !doneA, actB = (tau <= qtB) && !doneB;
;             if (actA || actB) {
;                 bf16x8 kf[4], vf[2][2];
; #pragma unroll
;                 for (int sp = 0; sp < 4; ++sp) kf[sp] = *(LAS bf16x8*)(lb + kra + kk * 32 * 144 + sp * 32);
; #pragma unroll
;                 for (int dd = 0; dd < 2; ++dd)
; #pragma unroll
;                     for (int s = 0; s < 2; ++s) vf[dd][s] = *(LAS bf16x8*)(lb + vra + dd * 32 * 144 + kk * 64 + s * 32);
;                 if (actA) { sub_tile_sb(kf, vf, qfA, oA0, oA1, RA, tau == qtA, r, h); if (__ballot(RA < 104.0f) == 0ull) doneA = true; }
.LBB0_443:
	s_cmp_gt_i32 s67, s65
	s_cselect_b64 s[72:73], -1, 0
	s_or_b64 s[72:73], s[72:73], s[56:57]
	s_and_b64 vcc, exec, s[72:73]
	s_cbranch_vccnz .LBB0_449
	ds_read_b128 v[2:5], v121
	ds_read_b128 v[6:9], v121 offset:32
	s_cmp_eq_u32 s68, 1
	s_cselect_b64 s[56:57], -1, 0
	s_cmp_lg_u32 s68, 1
	s_waitcnt lgkmcnt(1)
	v_mfma_f32_32x32x16_bf16 v[48:63], v[2:5], v[64:67], 0
	s_waitcnt lgkmcnt(0)
	v_mfma_f32_32x32x16_bf16 v[48:63], v[6:9], v[68:71], v[48:63]
	ds_read_b128 v[2:5], v121 offset:64
	ds_read_b128 v[6:9], v121 offset:96
	ds_read_b128 v[100:103], v120 offset:9216
	ds_read_b128 v[96:99], v120 offset:9248
	ds_read_b128 v[92:95], v120 offset:13824
	ds_read_b128 v[88:91], v120 offset:13856
	s_waitcnt lgkmcnt(5)
	v_mfma_f32_32x32x16_bf16 v[48:63], v[2:5], v[72:75], v[48:63]
	s_waitcnt lgkmcnt(4)
	v_mfma_f32_32x32x16_bf16 v[48:63], v[6:9], v[76:79], v[48:63]
	s_nop 11
	v_max_f32_e32 v0, v48, v48
	v_mul_f32_e64 v2, |v48|, s99
	v_mul_f32_e64 v4, |v49|, s99
	v_max_f32_e32 v14, 0, v0
	v_exp_f32_e32 v0, v2
	v_exp_f32_e32 v2, v4
	v_max_f32_e32 v3, v49, v49
	v_mul_f32_e64 v6, |v50|, s99
	v_mul_f32_e64 v115, |v53|, s99
	v_max_f32_e32 v15, 0, v3
	v_exp_f32_e32 v3, v6
	v_exp_f32_e32 v6, v115
	v_add_f32_e32 v2, 1.0, v2
	v_log_f32_e32 v121, v2
	v_mul_f32_e64 v2, |v54|, s99
	v_exp_f32_e32 v2, v2
	v_add_f32_e32 v0, 1.0, v0
	v_log_f32_e32 v120, v0
	v_add_f32_e32 v0, 1.0, v6
	v_mul_f32_e64 v8, |v51|, s99
	v_log_f32_e32 v125, v0
	v_max_f32_e32 v0, v54, v54
	v_exp_f32_e32 v4, v8
	v_max_f32_e32 v8, 0, v0
	v_add_f32_e32 v0, 1.0, v2
	v_mul_f32_e64 v2, |v55|, s99
	v_exp_f32_e32 v2, v2
	v_max_f32_e32 v9, v52, v52
	v_log_f32_e32 v126, v0
	v_max_f32_e32 v0, v55, v55
	v_max_f32_e32 v10, 0, v9
	v_max_f32_e32 v9, 0, v0
	v_add_f32_e32 v0, 1.0, v2
	v_mul_f32_e64 v2, |v56|, s99
	v_exp_f32_e32 v2, v2
	v_log_f32_e32 v127, v0
	v_max_f32_e32 v0, v56, v56
	v_max_f32_e32 v6, 0, v0
	v_add_f32_e32 v0, 1.0, v2
	v_mul_f32_e64 v2, |v57|, s99
	v_exp_f32_e32 v2, v2
	v_max_f32_e32 v7, v51, v51
	v_log_f32_e32 v128, v0
	v_max_f32_e32 v0, v57, v57
	v_max_f32_e32 v13, 0, v7
	v_max_f32_e32 v7, 0, v0
	v_add_f32_e32 v0, 1.0, v2
	v_mul_f32_e64 v2, |v58|, s99
	v_exp_f32_e32 v2, v2
	v_max_f32_e32 v5, v50, v50
	v_mul_f32_e64 v11, |v52|, s99
	v_add_f32_e32 v4, 1.0, v4
	v_log_f32_e32 v129, v0
	v_max_f32_e32 v0, v58, v58
	v_max_f32_e32 v12, 0, v5
	v_exp_f32_e32 v5, v11
	v_log_f32_e32 v123, v4
	v_max_f32_e32 v4, 0, v0
	v_add_f32_e32 v0, 1.0, v2
	v_mul_f32_e64 v2, |v59|, s99
	v_exp_f32_e32 v2, v2
	v_add_f32_e32 v5, 1.0, v5
	v_log_f32_e32 v130, v0
	v_max_f32_e32 v0, v59, v59
	v_add_f32_e32 v3, 1.0, v3
	v_log_f32_e32 v124, v5
	v_max_f32_e32 v5, 0, v0
	v_add_f32_e32 v0, 1.0, v2
	v_mul_f32_e64 v2, |v60|, s99
	v_log_f32_e32 v122, v3
	v_exp_f32_e32 v3, v2
	v_log_f32_e32 v131, v0
	v_max_f32_e32 v0, v60, v60
	v_max_f32_e32 v114, v53, v53
	v_max_f32_e32 v2, 0, v0
	v_add_f32_e32 v0, 1.0, v3
	v_mul_f32_e64 v3, |v61|, s99
	v_max_f32_e32 v11, 0, v114
	v_exp_f32_e32 v114, v3
	v_log_f32_e32 v132, v0
	v_max_f32_e32 v0, v61, v61
	v_max_f32_e32 v3, 0, v0
	v_add_f32_e32 v0, 1.0, v114
	v_log_f32_e32 v133, v0
	v_mul_f32_e64 v0, |v62|, s99
	v_exp_f32_e32 v0, v0
	v_mul_f32_e64 v114, |v63|, s99
	v_exp_f32_e32 v115, v114
	v_max_f32_e32 v134, v62, v62
	v_add_f32_e32 v0, 1.0, v0
	v_log_f32_e32 v114, v0
	v_add_f32_e32 v0, 1.0, v115
	v_log_f32_e32 v115, v0
	v_max_f32_e32 v0, v63, v63
	v_max_f32_e32 v134, 0, v134
	v_max_f32_e32 v135, 0, v0
	v_pk_fma_f32 v[114:115], v[114:115], s[96:97], v[134:135] op_sel_hi:[1,0,1]
	v_pk_fma_f32 v[2:3], v[132:133], s[96:97], v[2:3] op_sel_hi:[1,0,1]
	v_pk_fma_f32 v[4:5], v[130:131], s[96:97], v[4:5] op_sel_hi:[1,0,1]
	v_pk_fma_f32 v[6:7], v[128:129], s[96:97], v[6:7] op_sel_hi:[1,0,1]
	v_pk_fma_f32 v[8:9], v[126:127], s[96:97], v[8:9] op_sel_hi:[1,0,1]
	v_pk_fma_f32 v[10:11], v[124:125], s[96:97], v[10:11] op_sel_hi:[1,0,1]
	v_pk_fma_f32 v[12:13], v[122:123], s[96:97], v[12:13] op_sel_hi:[1,0,1]
	v_pk_fma_f32 v[14:15], v[120:121], s[96:97], v[14:15] op_sel_hi:[1,0,1]
	s_cbranch_scc1 .LBB0_446
	s_or_b64 vcc, s[42:43], s[40:41]
	v_cndmask_b32_e32 v114, 0, v114, vcc
	s_or_b64 vcc, vcc, s[38:39]
	v_cndmask_b32_e32 v3, 0, v3, vcc
	s_or_b64 vcc, vcc, s[36:37]
	v_cndmask_b32_e32 v2, 0, v2, vcc
	s_or_b64 vcc, vcc, s[34:35]
	v_cndmask_b32_e32 v5, 0, v5, vcc
	s_or_b64 vcc, vcc, s[30:31]
	v_cndmask_b32_e32 v4, 0, v4, vcc
	s_or_b64 vcc, vcc, s[28:29]
	v_cndmask_b32_e32 v7, 0, v7, vcc
	s_or_b64 vcc, vcc, s[26:27]
	v_cndmask_b32_e32 v6, 0, v6, vcc
	s_or_b64 vcc, vcc, s[24:25]
	v_cndmask_b32_e32 v9, 0, v9, vcc
	s_or_b64 vcc, vcc, s[22:23]
	v_cndmask_b32_e32 v8, 0, v8, vcc
	s_or_b64 vcc, vcc, s[20:21]
	v_cndmask_b32_e32 v11, 0, v11, vcc
	s_or_b64 vcc, vcc, s[18:19]
	v_cndmask_b32_e32 v10, 0, v10, vcc
	s_or_b64 vcc, vcc, s[16:17]
	v_cndmask_b32_e32 v13, 0, v13, vcc
	s_or_b64 vcc, vcc, s[14:15]
	v_cndmask_b32_e32 v12, 0, v12, vcc
	s_or_b64 vcc, vcc, s[12:13]
	v_cndmask_b32_e32 v15, 0, v15, vcc
	s_or_b64 vcc, vcc, s[10:11]
	v_cndmask_b32_e64 v115, 0, v115, s[42:43]
	v_cndmask_b32_e32 v14, 0, v14, vcc
